# sample_out_block epilogue preload also in the X3 instance
# baseline (speedup 1.0000x reference)
; __device__ __forceinline__ void sample_out_block(LAS unsigned char* lds, const bf16_t* A, const bf16_t* Bt, int K, bf16_t* xb, float* sspart, int blk, int tid) {
;     ...
;     {
;         const bf16_t* ap = A + (size_t)(r0 + l15) * K + wave * kq + 8 * g;
;         const bf16_t* bp = Bt + (size_t)(64 * cg + l15) * K + wave * kq + 8 * g;
;         bf16x8 af[2][2], bf[2][4], afn[2][2], bfn[2][4];
; #pragma unroll
;         for (int s = 0; s < 2; ++s) {
; #pragma unroll
;             for (int ra = 0; ra < 2; ++ra) af[s][ra] = *(const bf16x8*)(ap + (size_t)(16 * ra) * K + 32 * s);
; #pragma unroll
;             for (int nt = 0; nt < 4; ++nt) bf[s][nt] = *(const bf16x8*)(bp + (size_t)(16 * nt) * K + 32 * s);
;         }
;         for (int k0 = 0; k0 < kq; k0 += 64) {
;             const int k1 = (k0 + 64 < kq) ? k0 + 64 : k0;
; #pragma unroll
;             for (int s = 0; s < 2; ++s) {
; #pragma unroll
;                 for (int ra = 0; ra < 2; ++ra) afn[s][ra] = *(const bf16x8*)(ap + (size_t)(16 * ra) * K + k1 + 32 * s);
; #pragma unroll
;                 for (int nt = 0; nt < 4; ++nt) bfn[s][nt] = *(const bf16x8*)(bp + (size_t)(16 * nt) * K + k1 + 32 * s);
;             }
; #pragma unroll
;             for (int s = 0; s < 2; ++s)
; #pragma unroll
;                 for (int ra = 0; ra < 2; ++ra)
; #pragma unroll
;                     for (int nt = 0; nt < 4; ++nt) acc[ra][nt] = MFMA16(af[s][ra], bf[s][nt], acc[ra][nt]);
; #pragma unroll
;             for (int s = 0; s < 2; ++s) {
; #pragma unroll
;                 for (int ra = 0; ra < 2; ++ra) af[s][ra] = afn[s][ra];
; #pragma unroll
;                 for (int nt = 0; nt < 4; ++nt) bf[s][nt] = bfn[s][nt];
;             }
;         }
;     }
;     LAS f32x4* part = (LAS f32x4*)lds;
; #pragma unroll
;     for (int ra = 0; ra < 2; ++ra)
; #pragma unroll
;         for (int nt = 0; nt < 4; ++nt) part[(wave * 8 + ra * 4 + nt) * 64 + lane] = acc[ra][nt];
;     __syncthreads();
;     if (wave < 2) {
;         const int ra = wave;
;         f32x4 sum[4];
; #pragma unroll
;         for (int nt = 0; nt < 4; ++nt) {
;             sum[nt] = part[(0 * 8 + ra * 4 + nt) * 64 + lane];
; #pragma unroll
;             for (int w = 1; w < 8; ++w) sum[nt] += part[(w * 8 + ra * 4 + nt) * 64 + lane];
;         }
;         float ss[4] = {0.f, 0.f, 0.f, 0.f};
; #pragma unroll
;         for (int j = 0; j < 4; ++j)
; #pragma unroll
.LBB0_1463:
	s_and_b32 s19, s26, 0xffffffe0
	s_addk_i32 s19, 0x2000
	s_and_b32 s18, s26, 31
	v_or_b32_e32 v8, s19, v30
	v_ashrrev_i32_e32 v9, 31, v8
	s_lshl_b32 s20, s18, 6
	v_lshlrev_b64 v[8:9], 10, v[8:9]
	v_or_b32_e32 v0, s20, v30
	v_lshl_add_u64 v[28:29], v[2:3], 0, v[8:9]
	v_lshlrev_b32_e32 v0, 10, v0
	v_lshl_add_u64 v[42:43], v[4:5], 0, v[0:1]
	v_add_co_u32_e32 v66, vcc, 0x4000, v28
	s_mov_b64 s[8:9], vcc
	v_add_co_u32_e32 v24, vcc, 0x4000, v42
	global_load_dwordx4 v[8:11], v[28:29], off
	global_load_dwordx4 v[12:15], v[42:43], off
	v_addc_co_u32_e32 v25, vcc, 0, v43, vcc
	v_add_co_u32_e32 v50, vcc, 0x8000, v42
	global_load_dwordx4 v[16:19], v[24:25], off
	global_load_dwordx4 v[20:23], v[42:43], off offset:64
	v_addc_co_u32_e32 v51, vcc, 0, v43, vcc
	v_add_co_u32_e32 v58, vcc, 0xc000, v42
	global_load_dwordx4 v[24:27], v[24:25], off offset:64
	s_nop 0
	global_load_dwordx4 v[34:37], v[50:51], off
	v_addc_co_u32_e32 v59, vcc, 0, v43, vcc
	v_addc_co_u32_e64 v67, vcc, 0, v29, s[8:9]
	global_load_dwordx4 v[46:49], v[58:59], off
	s_nop 0
	global_load_dwordx4 v[50:53], v[50:51], off offset:64
	s_waitcnt vmcnt(6)
	v_mfma_f32_16x16x32_bf16 v[38:41], v[8:11], v[12:15], 0
	global_load_dwordx4 v[62:65], v[66:67], off
	s_nop 0
	global_load_dwordx4 v[58:61], v[58:59], off offset:64
	s_waitcnt vmcnt(7)
	v_mfma_f32_16x16x32_bf16 v[42:45], v[8:11], v[16:19], 0
	s_waitcnt vmcnt(4)
	v_mfma_f32_16x16x32_bf16 v[54:57], v[8:11], v[34:37], 0
	s_waitcnt vmcnt(3)
	v_mfma_f32_16x16x32_bf16 v[8:11], v[8:11], v[46:49], 0
	s_waitcnt vmcnt(1)
	v_mfma_f32_16x16x32_bf16 v[12:15], v[62:65], v[12:15], 0
	v_mfma_f32_16x16x32_bf16 v[16:19], v[62:65], v[16:19], 0
	v_mfma_f32_16x16x32_bf16 v[34:37], v[62:65], v[34:37], 0
	v_mfma_f32_16x16x32_bf16 v[46:49], v[62:65], v[46:49], 0
	global_load_dwordx4 v[62:65], v[28:29], off offset:64
	s_waitcnt vmcnt(0)
	v_mfma_f32_16x16x32_bf16 v[38:41], v[62:65], v[20:23], v[38:41]
	v_mfma_f32_16x16x32_bf16 v[42:45], v[62:65], v[24:27], v[42:45]
	v_mfma_f32_16x16x32_bf16 v[54:57], v[62:65], v[50:53], v[54:57]
	v_mfma_f32_16x16x32_bf16 v[8:11], v[62:65], v[58:61], v[8:11]
	global_load_dwordx4 v[62:65], v[66:67], off offset:64
	s_waitcnt vmcnt(0)
	v_mfma_f32_16x16x32_bf16 v[12:15], v[62:65], v[20:23], v[12:15]
	v_mfma_f32_16x16x32_bf16 v[16:19], v[62:65], v[24:27], v[16:19]
	v_mfma_f32_16x16x32_bf16 v[20:23], v[62:65], v[50:53], v[34:37]
	v_mfma_f32_16x16x32_bf16 v[24:27], v[62:65], v[58:61], v[46:49]
	ds_write_b128 v32, v[38:41]
	ds_write_b128 v32, v[42:45] offset:1024
	ds_write_b128 v32, v[54:57] offset:2048
	ds_write_b128 v32, v[8:11] offset:3072
	s_nop 0
	ds_write_b128 v32, v[12:15] offset:4096
	ds_write_b128 v32, v[16:19] offset:5120
	ds_write_b128 v32, v[20:23] offset:6144
	ds_write_b128 v32, v[24:27] offset:7168
	s_waitcnt lgkmcnt(0)
	s_barrier
	s_and_saveexec_b64 s[8:9], s[4:5]
	s_cbranch_execz .LBB0_1462
	v_add_u32_e32 v170, s19, v31
	v_lshlrev_b32_e32 v170, 12, v170
	s_lshl_b32 s36, s20, 1
	v_add_u32_e32 v170, s36, v170
	v_mov_b32_e32 v171, 0
	s_mov_b64 s[38:39], 0x1000
	v_lshl_add_u64 v[162:163], v[6:7], 0, v[170:171]
	v_lshl_add_u64 v[164:165], v[162:163], 0, s[38:39]
	v_lshl_add_u64 v[166:167], v[164:165], 0, s[38:39]
	v_lshl_add_u64 v[168:169], v[166:167], 0, s[38:39]
	global_load_ushort v146, v[162:163], off
	global_load_ushort v147, v[162:163], off offset:32
	global_load_ushort v148, v[162:163], off offset:64
	global_load_ushort v149, v[162:163], off offset:96
	global_load_ushort v150, v[164:165], off
	global_load_ushort v151, v[164:165], off offset:32
	global_load_ushort v152, v[164:165], off offset:64
	global_load_ushort v153, v[164:165], off offset:96
	global_load_ushort v154, v[166:167], off
	global_load_ushort v155, v[166:167], off offset:32
	global_load_ushort v156, v[166:167], off offset:64
	global_load_ushort v157, v[166:167], off offset:96
	global_load_ushort v158, v[168:169], off
	global_load_ushort v159, v[168:169], off offset:32
	global_load_ushort v160, v[168:169], off offset:64
	global_load_ushort v161, v[168:169], off offset:96
	ds_read_b128 v[8:11], v33
	ds_read_b128 v[12:15], v33 offset:8192
	s_lshl_b32 s80, s20, 1
	v_lshl_add_u64 v[28:29], v[6:7], 0, s[80:81]
	s_lshl_b32 s18, s18, 2
	s_add_u32 s18, s14, s18
	s_waitcnt lgkmcnt(0)
	v_pk_add_f32 v[14:15], v[10:11], v[14:15]
	v_pk_add_f32 v[12:13], v[8:9], v[12:13]
	ds_read_b128 v[8:11], v33 offset:16384
	s_waitcnt lgkmcnt(0)
	v_pk_add_f32 v[14:15], v[14:15], v[10:11]
	v_pk_add_f32 v[12:13], v[12:13], v[8:9]
	ds_read_b128 v[8:11], v33 offset:24576
	s_waitcnt lgkmcnt(0)
	v_pk_add_f32 v[14:15], v[14:15], v[10:11]
	v_pk_add_f32 v[12:13], v[12:13], v[8:9]
	ds_read_b128 v[8:11], v33 offset:32768
	s_waitcnt lgkmcnt(0)
	v_pk_add_f32 v[14:15], v[14:15], v[10:11]
	v_pk_add_f32 v[12:13], v[12:13], v[8:9]
	ds_read_b128 v[8:11], v33 offset:40960
	s_waitcnt lgkmcnt(0)
	v_pk_add_f32 v[14:15], v[14:15], v[10:11]
	v_pk_add_f32 v[12:13], v[12:13], v[8:9]
	ds_read_b128 v[8:11], v33 offset:49152
	s_waitcnt lgkmcnt(0)
	v_pk_add_f32 v[14:15], v[14:15], v[10:11]
	v_pk_add_f32 v[16:17], v[12:13], v[8:9]
	ds_read_b128 v[8:11], v33 offset:57344
	s_waitcnt lgkmcnt(0)
	v_pk_add_f32 v[12:13], v[14:15], v[10:11]
	v_pk_add_f32 v[20:21], v[16:17], v[8:9]
	ds_read_b128 v[8:11], v33 offset:1024
	ds_read_b128 v[14:17], v33 offset:9216
	s_waitcnt lgkmcnt(0)
	v_pk_add_f32 v[16:17], v[10:11], v[16:17]
	v_pk_add_f32 v[14:15], v[8:9], v[14:15]
	ds_read_b128 v[8:11], v33 offset:17408
	s_waitcnt lgkmcnt(0)
	v_pk_add_f32 v[16:17], v[16:17], v[10:11]
	v_pk_add_f32 v[14:15], v[14:15], v[8:9]
	ds_read_b128 v[8:11], v33 offset:25600
	s_waitcnt lgkmcnt(0)
; __device__ __forceinline__ float bf1(bf16_t h) { return __uint_as_float((unsigned)h << 16); }
; __device__ __forceinline__ bf16_t f2bf(float f) { return (bf16_t)(pk2(f, 0.f) & 0xffffu); }
; __device__ __forceinline__ void sample_out_block(LAS unsigned char* lds, const bf16_t* A, const bf16_t* Bt, int K, bf16_t* xb, float* sspart, int blk, int tid) {
;     ...
;         const int ra = wave;
;         f32x4 sum[4];
; #pragma unroll
;         for (int nt = 0; nt < 4; ++nt) {
;             sum[nt] = part[(0 * 8 + ra * 4 + nt) * 64 + lane];
; #pragma unroll
;             for (int w = 1; w < 8; ++w) sum[nt] += part[(w * 8 + ra * 4 + nt) * 64 + lane];
;         }
;         float ss[4] = {0.f, 0.f, 0.f, 0.f};
; #pragma unroll
;         for (int j = 0; j < 4; ++j)
; #pragma unroll
;             for (int nt = 0; nt < 4; ++nt) {
;                 bf16_t* xp = xb + (size_t)(r0 + 16 * ra + 4 * g + j) * 2048 + 64 * cg + 16 * nt + l15;
;                 const bf16_t nv = f2bf(bf1(*xp) + sum[nt][j]);
;                 *xp = nv; const float r = bf1(nv); ss[j] += r * r;
	v_pk_add_f32 v[16:17], v[16:17], v[10:11]
	v_pk_add_f32 v[14:15], v[14:15], v[8:9]
	ds_read_b128 v[8:11], v33 offset:33792
	s_waitcnt lgkmcnt(0)
	v_pk_add_f32 v[16:17], v[16:17], v[10:11]
	v_pk_add_f32 v[14:15], v[14:15], v[8:9]
	ds_read_b128 v[8:11], v33 offset:41984
	s_waitcnt lgkmcnt(0)
	v_pk_add_f32 v[16:17], v[16:17], v[10:11]
	v_pk_add_f32 v[14:15], v[14:15], v[8:9]
	ds_read_b128 v[8:11], v33 offset:50176
	s_waitcnt lgkmcnt(0)
	v_pk_add_f32 v[16:17], v[16:17], v[10:11]
	v_pk_add_f32 v[14:15], v[14:15], v[8:9]
	ds_read_b128 v[8:11], v33 offset:58368
	s_waitcnt lgkmcnt(0)
	v_pk_add_f32 v[18:19], v[16:17], v[10:11]
	v_pk_add_f32 v[26:27], v[14:15], v[8:9]
	ds_read_b128 v[8:11], v33 offset:2048
	ds_read_b128 v[14:17], v33 offset:10240
	s_waitcnt lgkmcnt(0)
	v_pk_add_f32 v[16:17], v[10:11], v[16:17]
	v_pk_add_f32 v[14:15], v[8:9], v[14:15]
	ds_read_b128 v[8:11], v33 offset:18432
	s_waitcnt lgkmcnt(0)
	v_pk_add_f32 v[16:17], v[16:17], v[10:11]
	v_pk_add_f32 v[14:15], v[14:15], v[8:9]
	ds_read_b128 v[8:11], v33 offset:26624
	s_waitcnt lgkmcnt(0)
	v_pk_add_f32 v[16:17], v[16:17], v[10:11]
	v_pk_add_f32 v[14:15], v[14:15], v[8:9]
	ds_read_b128 v[8:11], v33 offset:34816
	s_waitcnt lgkmcnt(0)
	v_pk_add_f32 v[16:17], v[16:17], v[10:11]
	v_pk_add_f32 v[14:15], v[14:15], v[8:9]
	ds_read_b128 v[8:11], v33 offset:43008
	s_waitcnt lgkmcnt(0)
	v_pk_add_f32 v[16:17], v[16:17], v[10:11]
	v_pk_add_f32 v[14:15], v[14:15], v[8:9]
	ds_read_b128 v[8:11], v33 offset:51200
	s_waitcnt lgkmcnt(0)
	v_pk_add_f32 v[16:17], v[16:17], v[10:11]
	v_pk_add_f32 v[14:15], v[14:15], v[8:9]
	ds_read_b128 v[8:11], v33 offset:59392
	s_waitcnt lgkmcnt(0)
	v_pk_add_f32 v[16:17], v[16:17], v[10:11]
	v_pk_add_f32 v[24:25], v[14:15], v[8:9]
	ds_read_b128 v[8:11], v33 offset:3072
	ds_read_b128 v[34:37], v33 offset:11264
	s_waitcnt lgkmcnt(0)
	v_pk_add_f32 v[14:15], v[10:11], v[36:37]
	v_pk_add_f32 v[22:23], v[8:9], v[34:35]
	ds_read_b128 v[8:11], v33 offset:19456
	ds_read_b128 v[34:37], v33 offset:60416
	s_waitcnt lgkmcnt(1)
	v_pk_add_f32 v[14:15], v[14:15], v[10:11]
	v_pk_add_f32 v[22:23], v[22:23], v[8:9]
	ds_read_b128 v[8:11], v33 offset:27648
	s_waitcnt lgkmcnt(0)
	v_pk_add_f32 v[14:15], v[14:15], v[10:11]
	v_pk_add_f32 v[22:23], v[22:23], v[8:9]
	ds_read_b128 v[8:11], v33 offset:35840
	s_waitcnt lgkmcnt(0)
	v_pk_add_f32 v[14:15], v[14:15], v[10:11]
	v_pk_add_f32 v[22:23], v[22:23], v[8:9]
	ds_read_b128 v[8:11], v33 offset:44032
	s_waitcnt lgkmcnt(0)
	v_pk_add_f32 v[14:15], v[14:15], v[10:11]
	v_pk_add_f32 v[22:23], v[22:23], v[8:9]
	ds_read_b128 v[8:11], v33 offset:52224
	s_waitcnt lgkmcnt(0)
	v_pk_add_f32 v[10:11], v[14:15], v[10:11]
	v_pk_add_f32 v[14:15], v[22:23], v[8:9]
	v_pk_add_f32 v[8:9], v[10:11], v[36:37]
	v_add_u32_e32 v10, s19, v31
	v_ashrrev_i32_e32 v11, 31, v10
	v_pk_add_f32 v[22:23], v[14:15], v[34:35]
	v_lshlrev_b64 v[14:15], 12, v[10:11]
	v_lshl_add_u64 v[14:15], v[28:29], 0, v[14:15]
	s_waitcnt vmcnt(0)
	v_mov_b32_e32 v0, v146
	s_addc_u32 s19, s15, 0
	s_waitcnt vmcnt(0)
; __device__ __forceinline__ float bf1(bf16_t h) { return __uint_as_float((unsigned)h << 16); }
; __device__ __forceinline__ bf16_t f2bf(float f) { return (bf16_t)(pk2(f, 0.f) & 0xffffu); }
; __device__ __forceinline__ void sample_out_block(LAS unsigned char* lds, const bf16_t* A, const bf16_t* Bt, int K, bf16_t* xb, float* sspart, int blk, int tid) {
;     ...
;         for (int j = 0; j < 4; ++j)
; #pragma unroll
;             for (int nt = 0; nt < 4; ++nt) {
;                 bf16_t* xp = xb + (size_t)(r0 + 16 * ra + 4 * g + j) * 2048 + 64 * cg + 16 * nt + l15;
;                 const bf16_t nv = f2bf(bf1(*xp) + sum[nt][j]);
;                 *xp = nv; const float r = bf1(nv); ss[j] += r * r;
;             }
; #pragma unroll
;         for (int j = 0; j < 4; ++j) {
;             float s = ss[j];
;             s += __shfl_xor(s, 1); s += __shfl_xor(s, 2); s += __shfl_xor(s, 4); s += __shfl_xor(s, 8);
;             if (l15 == 0) sspart[(size_t)(r0 + 16 * ra + 4 * g + j) * 32 + cg] = s;
;         }
	v_lshlrev_b32_e32 v0, 16, v0
	v_add_f32_e32 v0, v20, v0
	v_cvt_pk_bf16_f32 v0, v0, s0
	global_store_short v[14:15], v0, off
	v_lshlrev_b32_e32 v20, 16, v0
	v_mov_b32_e32 v0, v147
	v_lshlrev_b32_e32 v0, 16, v0
	v_add_f32_e32 v0, v26, v0
	v_cvt_pk_bf16_f32 v0, v0, s0
	global_store_short v[14:15], v0, off offset:32
	v_lshlrev_b32_e32 v0, 16, v0
	v_mul_f32_e32 v0, v0, v0
	v_fmac_f32_e32 v0, v20, v20
	v_mov_b32_e32 v20, v148
	v_lshlrev_b32_e32 v20, 16, v20
	v_add_f32_e32 v20, v24, v20
	v_cvt_pk_bf16_f32 v20, v20, s0
	global_store_short v[14:15], v20, off offset:64
	v_lshlrev_b32_e32 v20, 16, v20
	v_fmac_f32_e32 v0, v20, v20
	v_mov_b32_e32 v20, v149
	v_lshlrev_b32_e32 v20, 16, v20
	v_add_f32_e32 v20, v22, v20
	v_cvt_pk_bf16_f32 v20, v20, s0
	global_store_short v[14:15], v20, off offset:96
	v_lshlrev_b32_e32 v14, 16, v20
	v_fmac_f32_e32 v0, v14, v14
	v_or_b32_e32 v14, 1, v10
	v_ashrrev_i32_e32 v15, 31, v14
	v_lshlrev_b64 v[34:35], 12, v[14:15]
	v_lshl_add_u64 v[36:37], v[28:29], 0, v[34:35]
	v_mov_b32_e32 v20, v150
	v_lshlrev_b32_e32 v20, 16, v20
	v_add_f32_e32 v20, v21, v20
	v_cvt_pk_bf16_f32 v26, v20, s0
	v_mov_b32_e32 v20, v151
	v_lshlrev_b32_e32 v20, 16, v20
	v_add_f32_e32 v20, v27, v20
	v_cvt_pk_bf16_f32 v27, v20, s0
	v_mov_b32_e32 v20, v152
	v_lshlrev_b32_e32 v20, 16, v20
	v_add_f32_e32 v20, v25, v20
	v_cvt_pk_bf16_f32 v34, v20, s0
	v_mov_b32_e32 v20, v153
	v_lshlrev_b32_e32 v20, 16, v20
	v_add_f32_e32 v20, v23, v20
	v_cvt_pk_bf16_f32 v35, v20, s0
	v_or_b32_e32 v20, 2, v10
	v_ashrrev_i32_e32 v21, 31, v20
	v_lshlrev_b64 v[22:23], 12, v[20:21]
	v_lshl_add_u64 v[22:23], v[28:29], 0, v[22:23]
	v_mov_b32_e32 v24, v154
	v_lshlrev_b32_e32 v24, 16, v24
	v_add_f32_e32 v12, v12, v24
	v_mov_b32_e32 v24, v155
	v_cvt_pk_bf16_f32 v12, v12, s0
	global_store_short v[22:23], v12, off
	global_store_short v[36:37], v26, off
	global_store_short v[36:37], v27, off offset:32
	global_store_short v[36:37], v34, off offset:64
	global_store_short v[36:37], v35, off offset:96
	v_xor_b32_e32 v36, 8, v215
	s_waitcnt vmcnt(5)
	v_lshlrev_b32_e32 v24, 16, v24
	v_add_f32_e32 v18, v18, v24
	v_mov_b32_e32 v24, v156
	v_cvt_pk_bf16_f32 v18, v18, s0
	global_store_short v[22:23], v18, off offset:32
	s_waitcnt vmcnt(1)
	v_lshlrev_b32_e32 v24, 16, v24
	v_add_f32_e32 v16, v16, v24
	v_mov_b32_e32 v24, v157
	v_cvt_pk_bf16_f32 v16, v16, s0
	global_store_short v[22:23], v16, off offset:64
	s_waitcnt vmcnt(1)
	v_lshlrev_b32_e32 v24, 16, v24
	v_add_f32_e32 v8, v8, v24
	v_cvt_pk_bf16_f32 v8, v8, s0
	global_store_short v[22:23], v8, off offset:96
	v_or_b32_e32 v22, 3, v10
	v_ashrrev_i32_e32 v23, 31, v22
	v_lshlrev_b64 v[24:25], 12, v[22:23]
	v_lshl_add_u64 v[24:25], v[28:29], 0, v[24:25]
	v_mov_b32_e32 v28, v158
	v_lshlrev_b32_e32 v28, 16, v28
	v_add_f32_e32 v13, v13, v28
	v_mov_b32_e32 v28, v159
	v_cvt_pk_bf16_f32 v13, v13, s0
	global_store_short v[24:25], v13, off
	s_waitcnt vmcnt(1)
	v_lshlrev_b32_e32 v28, 16, v28
	v_add_f32_e32 v19, v19, v28
	v_mov_b32_e32 v28, v160
	v_cvt_pk_bf16_f32 v19, v19, s0
	global_store_short v[24:25], v19, off offset:32
	s_waitcnt vmcnt(1)
	v_lshlrev_b32_e32 v28, 16, v28
	v_add_f32_e32 v17, v17, v28
	v_mov_b32_e32 v28, v161
	v_cvt_pk_bf16_f32 v17, v17, s0
	global_store_short v[24:25], v17, off offset:64
	s_waitcnt vmcnt(1)
	v_lshlrev_b32_e32 v28, 16, v28
	v_add_f32_e32 v9, v9, v28
	v_cvt_pk_bf16_f32 v9, v9, s0
	global_store_short v[24:25], v9, off offset:96
	v_and_b32_e32 v25, 64, v215
	v_xor_b32_e32 v24, 1, v215
	v_add_u32_e32 v29, 64, v25
	v_cmp_lt_i32_e32 vcc, v24, v29
	v_xor_b32_e32 v25, 2, v215
	v_xor_b32_e32 v28, 4, v215
	v_cndmask_b32_e32 v24, v215, v24, vcc
	v_cmp_lt_i32_e32 vcc, v25, v29
	v_lshlrev_b32_e32 v24, 2, v24
	s_nop 0
	v_cndmask_b32_e32 v25, v215, v25, vcc
	v_cmp_lt_i32_e32 vcc, v28, v29
	v_lshlrev_b32_e32 v25, 2, v25
	s_nop 0
	v_cndmask_b32_e32 v28, v215, v28, vcc
	v_cmp_lt_i32_e32 vcc, v36, v29
	v_lshlrev_b32_e32 v28, 2, v28
	s_nop 0
	v_cndmask_b32_e32 v29, v215, v36, vcc
	ds_bpermute_b32 v36, v24, v0
	v_lshlrev_b32_e32 v29, 2, v29
	s_waitcnt lgkmcnt(0)
	v_add_f32_e32 v0, v0, v36
	ds_bpermute_b32 v36, v25, v0
	s_waitcnt lgkmcnt(0)
	v_add_f32_e32 v0, v0, v36
	ds_bpermute_b32 v36, v28, v0
	s_waitcnt lgkmcnt(0)
	v_add_f32_e32 v0, v0, v36
	ds_bpermute_b32 v36, v29, v0
	s_and_saveexec_b64 s[20:21], s[6:7]
	s_cbranch_execz .LBB0_1466
	v_lshlrev_b64 v[10:11], 7, v[10:11]
	v_lshl_add_u64 v[10:11], s[18:19], 0, v[10:11]
	s_waitcnt lgkmcnt(0)
	v_add_f32_e32 v0, v0, v36
	global_store_dword v[10:11], v0, off
